# fused-norm epilogue: post-norm gain loads issued ahead of the first row-statistics collect (latency hides behind the exchange); slot load retargeted to free registers
# speedup vs baseline: 1.0040x; 1.0012x over previous
; #define PG8_LAS __attribute__((address_space(3)))
; __device__ __forceinline__ void panel_ss_collect(const Unit& u, PG8_LAS unsigned char* lds, int wid, int lane, float* slots, unsigned* cnt, unsigned target) {
;     PG8_LAS float* S = (PG8_LAS float*)(lds + 4096);
;     const int row = wid * 32 + (lane & 31);
;     if (wid == 0) { unsigned sp = 0;
;         while ((unsigned)__builtin_amdgcn_readfirstlane(__hip_atomic_load(cnt + 64 * u.pm, __ATOMIC_RELAXED, __HIP_MEMORY_SCOPE_AGENT)) < target) { __builtin_amdgcn_s_sleep(2); if (++sp > (1u << 22)) break; }
;         __builtin_amdgcn_fence(__ATOMIC_ACQUIRE, "agent"); }
;     __device__ __forceinline__ void run(f32x4 (&acc)[2][2][4][2], const Unit& u, int wr, int wc, int fr, int fq, PG8_LAS unsigned char* lds, int wid, int lane) const {
;     ...
;         u32x4 pre[2][4][2];
; #pragma unroll
;         for (int ai = 0; ai < 2; ++ai)
; #pragma unroll
;             for (int m = 0; m < 4; ++m) { const size_t off = (size_t)(u.pm * BM + ai * HALF + wr * 64 + m * 16 + fr) * 1024 + col0;
; #pragma unroll
;                 for (int bj = 0; bj < 2; ++bj) pre[ai][m][bj] = *(const u32x4*)(xb + off + bj * HALF); }
;         panel_ss_collect(u, lds, wid, lane, slots1, cnt1, target);
;         { f32x4 g[2][2];
; #pragma unroll
;           for (int bj = 0; bj < 2; ++bj)
; #pragma unroll
;               for (int n = 0; n < 2; ++n) g[bj][n] = *(const f32x4*)(g_post + col0 + bj * HALF + 4 * n);
.LBB0_168:
	s_or_b64 exec, exec, s[0:1]
	s_lshl_b32 s0, s28, 8
	s_or_b32 s0, s0, s30
	v_or_b32_e32 v212, s0, v176
	s_lshl_b32 s12, s56, 8
	v_add_u32_e32 v222, s12, v237
	v_ashrrev_i32_e32 v213, 31, v212
	s_waitcnt lgkmcnt(0)
	v_lshl_add_u64 v[130:131], v[212:213], 1, s[96:97]
	s_mov_b64 s[0:1], 0x11900000
	v_ashrrev_i32_e32 v223, 31, v222
	v_lshl_add_u64 v[210:211], v[130:131], 0, s[0:1]
	v_lshlrev_b64 v[130:131], 11, v[222:223]
	v_lshl_add_u64 v[130:131], v[210:211], 0, v[130:131]
	global_load_dwordx4 v[206:209], v[130:131], off
	global_load_dwordx4 v[202:205], v[130:131], off offset:256
	v_or_b32_e32 v130, 16, v222
	v_ashrrev_i32_e32 v131, 31, v130
	v_lshlrev_b64 v[130:131], 11, v[130:131]
	v_lshl_add_u64 v[130:131], v[210:211], 0, v[130:131]
	global_load_dwordx4 v[198:201], v[130:131], off
	global_load_dwordx4 v[194:197], v[130:131], off offset:256
	v_or_b32_e32 v130, 32, v222
	v_ashrrev_i32_e32 v131, 31, v130
	v_lshlrev_b64 v[130:131], 11, v[130:131]
	v_lshl_add_u64 v[130:131], v[210:211], 0, v[130:131]
	global_load_dwordx4 v[190:193], v[130:131], off
	global_load_dwordx4 v[186:189], v[130:131], off offset:256
	v_or_b32_e32 v130, 48, v222
	v_ashrrev_i32_e32 v131, 31, v130
	v_lshlrev_b64 v[130:131], 11, v[130:131]
	v_add_u32_e32 v220, 0x80, v222
	v_lshl_add_u64 v[130:131], v[210:211], 0, v[130:131]
	v_ashrrev_i32_e32 v221, 31, v220
	global_load_dwordx4 v[182:185], v[130:131], off
	global_load_dwordx4 v[178:181], v[130:131], off offset:256
	v_lshlrev_b64 v[130:131], 11, v[220:221]
	v_add_u32_e32 v218, 0x90, v222
	v_lshl_add_u64 v[130:131], v[210:211], 0, v[130:131]
	v_ashrrev_i32_e32 v219, 31, v218
	global_load_dwordx4 v[174:177], v[130:131], off
	global_load_dwordx4 v[170:173], v[130:131], off offset:256
	v_lshlrev_b64 v[130:131], 11, v[218:219]
	v_add_u32_e32 v216, 0xa0, v222
	v_lshl_add_u64 v[130:131], v[210:211], 0, v[130:131]
	v_ashrrev_i32_e32 v217, 31, v216
	global_load_dwordx4 v[166:169], v[130:131], off
	global_load_dwordx4 v[162:165], v[130:131], off offset:256
	v_lshlrev_b64 v[130:131], 11, v[216:217]
	v_add_u32_e32 v214, 0xb0, v222
	v_lshl_add_u64 v[130:131], v[210:211], 0, v[130:131]
	v_ashrrev_i32_e32 v215, 31, v214
	global_load_dwordx4 v[146:149], v[130:131], off
	global_load_dwordx4 v[138:141], v[130:131], off offset:256
	v_lshlrev_b64 v[130:131], 11, v[214:215]
	v_lshl_add_u64 v[130:131], v[210:211], 0, v[130:131]
	global_load_dwordx4 v[134:137], v[130:131], off
	s_nop 0
	global_load_dwordx4 v[130:133], v[130:131], off offset:256
	v_lshl_add_u64 v[150:151], v[212:213], 2, s[14:15]
	global_load_dwordx4 v[154:157], v[150:151], off offset:16
	global_load_dwordx4 v[158:161], v[150:151], off
	global_load_dwordx4 v[142:145], v[150:151], off offset:528
	s_nop 0
	global_load_dwordx4 v[150:153], v[150:151], off offset:512
	s_cmp_lt_u32 s4, 64
	s_cselect_b64 s[0:1], -1, 0
	s_cmp_gt_u32 s4, 63
	s_cbranch_scc1 .LBB0_178
	s_lshl_b32 s18, s56, 6
	s_ashr_i32 s19, s18, 31
	s_lshl_b64 s[18:19], s[18:19], 2
	s_add_u32 s18, s29, s18
	s_addc_u32 s19, s34, s19
	s_mov_b32 s29, 0x400001
	s_branch .LBB0_171

; __device__ __forceinline__ void panel_ss_collect(const Unit& u, PG8_LAS unsigned char* lds, int wid, int lane, float* slots, unsigned* cnt, unsigned target) {
;     ...
;     asm volatile("s_waitcnt vmcnt(0) lgkmcnt(0)" ::: "memory"); __builtin_amdgcn_s_barrier(); asm volatile("" ::: "memory");
;     if (lane < 32) { const float* sl = slots + (size_t)(u.pm * BM + row) * 4; float t = 0.f;
; #pragma unroll
;         for (int q = 0; q < 4; ++q) t += __hip_atomic_load(sl + q, __ATOMIC_RELAXED, __HIP_MEMORY_SCOPE_AGENT);
;         S[row] = t; }
;     __device__ __forceinline__ void run(f32x4 (&acc)[2][2][4][2], const Unit& u, int wr, int wc, int fr, int fq, PG8_LAS unsigned char* lds, int wid, int lane) const {
;     ...
; #pragma unroll
;           for (int ai = 0; ai < 2; ++ai)
; #pragma unroll
;               for (int m = 0; m < 4; ++m) { const int r = ai * HALF + wr * 64 + m * 16 + fr; const float rs = coef / sqrtf(S[r] * (1.0f / 1024.0f) + 1e-6f);
; #pragma unroll
;                   for (int bj = 0; bj < 2; ++bj) { f32x4 x0, x1; unpack8(pre[ai][m][bj], x0, x1);
;                       acc[ai][bj][m][0] = x0 + acc[ai][bj][m][0] * g[bj][0] * rs; acc[ai][bj][m][1] = x1 + acc[ai][bj][m][1] * g[bj][1] * rs; } } }
.LBB0_178:
	s_waitcnt vmcnt(0) lgkmcnt(0)
	s_barrier
	s_lshl_b32 s29, s5, 5
	v_and_or_b32 v242, v236, 31, s29
	s_and_saveexec_b64 s[18:19], s[8:9]
	s_cbranch_execz .LBB0_180
	v_add_u32_e32 v252, s12, v242
	v_ashrrev_i32_e32 v253, 31, v252
	v_lshl_add_u64 v[252:253], v[252:253], 4, s[2:3]
	global_load_dwordx4 v[248:251], v[252:253], off sc1
	s_waitcnt vmcnt(0)
	v_add_f32_e32 v0, 0, v248
	v_add_f32_e32 v0, v0, v249
	v_add_f32_e32 v0, v0, v250
	v_add_f32_e32 v0, v0, v251
	v_lshl_add_u32 v252, v242, 2, 0
	ds_write_b32 v252, v0 offset:4096
.LBB0_180:
	s_or_b64 exec, exec, s[18:19]
	s_waitcnt lgkmcnt(0)
	s_barrier
	s_add_u32 s2, s96, 0x15b00000
	s_addc_u32 s3, s97, 0
	s_add_u32 s5, s96, 0x15908000
	s_addc_u32 s34, s97, 0
	s_and_b32 s4, s4, 0xffffff00
	s_add_i32 s4, s4, 0
	v_lshl_add_u32 v0, v238, 2, s4
	v_add_u32_e32 v243, 0x1000, v0
	ds_read2_b32 v[224:225], v243 offset1:16
	s_cmp_eq_u64 s[22:23], 0
	s_cselect_b64 s[18:19], -1, 0
	s_cmp_lg_u64 s[22:23], 0
	s_waitcnt lgkmcnt(0)
	v_fmamk_f32 v0, v224, 0x3a800000, v230
	v_cmp_gt_f32_e32 vcc, s80, v0
	v_mul_f32_e32 v224, 0x4f800000, v0
	s_waitcnt vmcnt(0)
	v_pk_mul_f32 v[124:125], v[124:125], v[156:157]
	v_cndmask_b32_e32 v0, v0, v224, vcc
	v_sqrt_f32_e32 v224, v0
	v_pk_mul_f32 v[128:129], v[128:129], v[160:161]
	v_pk_mul_f32 v[126:127], v[126:127], v[158:159]
	v_pk_mul_f32 v[122:123], v[122:123], v[154:155]
	v_add_u32_e32 v244, -1, v224
	v_fma_f32 v245, -v244, v224, v0
	v_cmp_ge_f32_e64 s[14:15], 0, v245
	v_add_u32_e32 v245, 1, v224
	v_pk_mul_f32 v[120:121], v[120:121], v[152:153]
	v_cndmask_b32_e64 v244, v224, v244, s[14:15]
	v_fma_f32 v224, -v245, v224, v0
	v_cmp_lt_f32_e64 s[14:15], 0, v224
	v_pk_mul_f32 v[118:119], v[118:119], v[150:151]
	v_pk_mul_f32 v[116:117], v[116:117], v[144:145]
	v_cndmask_b32_e64 v224, v244, v245, s[14:15]
	v_mul_f32_e32 v244, 0x37800000, v224
	v_cndmask_b32_e32 v224, v224, v244, vcc
	v_cmp_class_f32_e32 vcc, v0, v231
	v_pk_mul_f32 v[114:115], v[114:115], v[142:143]
	v_pk_mul_f32 v[112:113], v[112:113], v[160:161]
	v_cndmask_b32_e32 v0, v224, v0, vcc
	v_div_scale_f32 v224, s[14:15], v0, v0, s31
	v_rcp_f32_e32 v244, v224
	v_pk_mul_f32 v[104:105], v[104:105], v[152:153]
	v_pk_mul_f32 v[108:109], v[108:109], v[156:157]
	v_pk_mul_f32 v[110:111], v[110:111], v[158:159]
	v_fma_f32 v245, -v224, v244, 1.0
	v_fmac_f32_e32 v244, v245, v244
	v_div_scale_f32 v245, vcc, s31, v0, s31
	v_mul_f32_e32 v246, v245, v244
	v_fma_f32 v247, -v224, v246, v245
	v_fmac_f32_e32 v246, v247, v244
	v_fma_f32 v224, -v224, v246, v245
	v_div_fmas_f32 v224, v224, v244, v246
	v_div_fixup_f32 v0, v224, v0, s31
	v_lshlrev_b32_e32 v244, 16, v206
	v_and_b32_e32 v245, 0xffff0000, v206
	v_lshlrev_b32_e32 v206, 16, v207
	v_and_b32_e32 v207, 0xffff0000, v207
	v_lshlrev_b32_e32 v246, 16, v208
	v_and_b32_e32 v247, 0xffff0000, v208
	v_lshlrev_b32_e32 v208, 16, v209
	v_and_b32_e32 v209, 0xffff0000, v209
	v_pk_fma_f32 v[128:129], v[128:129], v[0:1], v[206:207] op_sel_hi:[1,0,1]
	v_pk_fma_f32 v[124:125], v[124:125], v[0:1], v[208:209] op_sel_hi:[1,0,1]
	v_lshlrev_b32_e32 v206, 16, v202
	v_and_b32_e32 v207, 0xffff0000, v202
	v_lshlrev_b32_e32 v202, 16, v203
	v_and_b32_e32 v203, 0xffff0000, v203
	v_lshlrev_b32_e32 v208, 16, v204
	v_and_b32_e32 v209, 0xffff0000, v204
	v_lshlrev_b32_e32 v204, 16, v205
	v_and_b32_e32 v205, 0xffff0000, v205
	v_pk_fma_f32 v[126:127], v[126:127], v[0:1], v[244:245] op_sel_hi:[1,0,1]
	v_pk_fma_f32 v[122:123], v[122:123], v[0:1], v[246:247] op_sel_hi:[1,0,1]
	v_pk_fma_f32 v[120:121], v[120:121], v[0:1], v[202:203] op_sel_hi:[1,0,1]
	v_pk_fma_f32 v[118:119], v[118:119], v[0:1], v[206:207] op_sel_hi:[1,0,1]
	v_pk_fma_f32 v[116:117], v[116:117], v[0:1], v[204:205] op_sel_hi:[1,0,1]
	v_pk_fma_f32 v[114:115], v[114:115], v[0:1], v[208:209] op_sel_hi:[1,0,1]
	v_fmamk_f32 v0, v225, 0x3a800000, v230
	v_cmp_gt_f32_e32 vcc, s80, v0
	v_mul_f32_e32 v202, 0x4f800000, v0
	v_pk_mul_f32 v[106:107], v[106:107], v[154:155]
	v_cndmask_b32_e32 v0, v0, v202, vcc
	v_sqrt_f32_e32 v202, v0
	v_pk_mul_f32 v[102:103], v[102:103], v[150:151]
	v_pk_mul_f32 v[100:101], v[100:101], v[144:145]
	v_pk_mul_f32 v[98:99], v[98:99], v[142:143]
	v_add_u32_e32 v203, -1, v202
	v_fma_f32 v204, -v203, v202, v0
	v_cmp_ge_f32_e64 s[14:15], 0, v204
	v_add_u32_e32 v204, 1, v202
	v_pk_mul_f32 v[96:97], v[96:97], v[160:161]
	v_cndmask_b32_e64 v203, v202, v203, s[14:15]
	v_fma_f32 v202, -v204, v202, v0
	v_cmp_lt_f32_e64 s[14:15], 0, v202
	v_pk_mul_f32 v[92:93], v[92:93], v[156:157]
	v_pk_mul_f32 v[94:95], v[94:95], v[158:159]
	v_cndmask_b32_e64 v202, v203, v204, s[14:15]
	v_mul_f32_e32 v203, 0x37800000, v202
	v_cndmask_b32_e32 v202, v202, v203, vcc
	v_cmp_class_f32_e32 vcc, v0, v231
	v_pk_mul_f32 v[90:91], v[90:91], v[154:155]
	v_pk_mul_f32 v[88:89], v[88:89], v[152:153]
	v_cndmask_b32_e32 v0, v202, v0, vcc
	v_div_scale_f32 v202, s[14:15], v0, v0, s31
	v_rcp_f32_e32 v203, v202
	v_pk_mul_f32 v[86:87], v[86:87], v[150:151]
	v_pk_mul_f32 v[84:85], v[84:85], v[144:145]
	v_pk_mul_f32 v[82:83], v[82:83], v[142:143]
	v_fma_f32 v204, -v202, v203, 1.0
	v_fmac_f32_e32 v203, v204, v203
	v_div_scale_f32 v204, vcc, s31, v0, s31
	v_mul_f32_e32 v205, v204, v203
	v_fma_f32 v206, -v202, v205, v204
	v_fmac_f32_e32 v205, v206, v203
	v_fma_f32 v202, -v202, v205, v204
	v_div_fmas_f32 v202, v202, v203, v205
	v_div_fixup_f32 v0, v202, v0, s31
	v_lshlrev_b32_e32 v202, 16, v198
	v_and_b32_e32 v203, 0xffff0000, v198
	v_lshlrev_b32_e32 v198, 16, v199
	v_and_b32_e32 v199, 0xffff0000, v199
	v_pk_fma_f32 v[112:113], v[112:113], v[0:1], v[198:199] op_sel_hi:[1,0,1]
	v_lshlrev_b32_e32 v198, 16, v194
	v_and_b32_e32 v199, 0xffff0000, v194
	v_lshlrev_b32_e32 v194, 16, v195
	v_and_b32_e32 v195, 0xffff0000, v195
	v_pk_fma_f32 v[104:105], v[104:105], v[0:1], v[194:195] op_sel_hi:[1,0,1]
	ds_read2_b32 v[194:195], v243 offset0:32 offset1:48
	v_lshlrev_b32_e32 v204, 16, v200
	v_and_b32_e32 v205, 0xffff0000, v200
	v_lshlrev_b32_e32 v200, 16, v201
	v_and_b32_e32 v201, 0xffff0000, v201
	v_pk_fma_f32 v[108:109], v[108:109], v[0:1], v[200:201] op_sel_hi:[1,0,1]
	v_lshlrev_b32_e32 v200, 16, v196
	v_and_b32_e32 v201, 0xffff0000, v196
	v_lshlrev_b32_e32 v196, 16, v197
	v_and_b32_e32 v197, 0xffff0000, v197
	v_pk_fma_f32 v[110:111], v[110:111], v[0:1], v[202:203] op_sel_hi:[1,0,1]
	v_pk_fma_f32 v[106:107], v[106:107], v[0:1], v[204:205] op_sel_hi:[1,0,1]
	v_pk_fma_f32 v[102:103], v[102:103], v[0:1], v[198:199] op_sel_hi:[1,0,1]
	v_pk_fma_f32 v[100:101], v[100:101], v[0:1], v[196:197] op_sel_hi:[1,0,1]
	v_pk_fma_f32 v[98:99], v[98:99], v[0:1], v[200:201] op_sel_hi:[1,0,1]
	s_waitcnt lgkmcnt(0)
;     __device__ __forceinline__ void run(f32x4 (&acc)[2][2][4][2], const Unit& u, int wr, int wc, int fr, int fq, PG8_LAS unsigned char* lds, int wid, int lane) const {
;     ...
;           for (int ai = 0; ai < 2; ++ai)
; #pragma unroll
;               for (int m = 0; m < 4; ++m) { const int r = ai * HALF + wr * 64 + m * 16 + fr; const float rs = coef / sqrtf(S[r] * (1.0f / 1024.0f) + 1e-6f);
; #pragma unroll
;                   for (int bj = 0; bj < 2; ++bj) { f32x4 x0, x1; unpack8(pre[ai][m][bj], x0, x1);
;                       acc[ai][bj][m][0] = x0 + acc[ai][bj][m][0] * g[bj][0] * rs; acc[ai][bj][m][1] = x1 + acc[ai][bj][m][1] * g[bj][1] * rs; } } }
	v_fmamk_f32 v0, v194, 0x3a800000, v230
	v_cmp_gt_f32_e32 vcc, s80, v0
	v_mul_f32_e32 v194, 0x4f800000, v0
	v_pk_mul_f32 v[80:81], v[80:81], v[160:161]
	v_cndmask_b32_e32 v0, v0, v194, vcc
	v_sqrt_f32_e32 v194, v0
	v_pk_mul_f32 v[72:73], v[72:73], v[152:153]
	v_pk_mul_f32 v[76:77], v[76:77], v[156:157]
	v_pk_mul_f32 v[78:79], v[78:79], v[158:159]
	v_add_u32_e32 v196, -1, v194
	v_fma_f32 v197, -v196, v194, v0
	v_cmp_ge_f32_e64 s[14:15], 0, v197
	v_add_u32_e32 v197, 1, v194
	v_pk_mul_f32 v[74:75], v[74:75], v[154:155]
	v_cndmask_b32_e64 v196, v194, v196, s[14:15]
	v_fma_f32 v194, -v197, v194, v0
	v_cmp_lt_f32_e64 s[14:15], 0, v194
	v_pk_mul_f32 v[70:71], v[70:71], v[150:151]
	v_pk_mul_f32 v[68:69], v[68:69], v[144:145]
	v_cndmask_b32_e64 v194, v196, v197, s[14:15]
	v_mul_f32_e32 v196, 0x37800000, v194
	v_cndmask_b32_e32 v194, v194, v196, vcc
	v_cmp_class_f32_e32 vcc, v0, v231
	v_pk_mul_f32 v[66:67], v[66:67], v[142:143]
	v_pk_mul_f32 v[64:65], v[64:65], v[160:161]
	v_cndmask_b32_e32 v0, v194, v0, vcc
	v_div_scale_f32 v194, s[14:15], v0, v0, s31
	v_rcp_f32_e32 v196, v194
	v_pk_mul_f32 v[60:61], v[60:61], v[156:157]
	v_pk_mul_f32 v[62:63], v[62:63], v[158:159]
	v_pk_mul_f32 v[58:59], v[58:59], v[154:155]
	v_fma_f32 v197, -v194, v196, 1.0
	v_fmac_f32_e32 v196, v197, v196
	v_div_scale_f32 v197, vcc, s31, v0, s31
	v_mul_f32_e32 v198, v197, v196
	v_fma_f32 v199, -v194, v198, v197
	v_fmac_f32_e32 v198, v199, v196
	v_fma_f32 v194, -v194, v198, v197
	v_div_fmas_f32 v194, v194, v196, v198
	v_div_fixup_f32 v0, v194, v0, s31
	v_lshlrev_b32_e32 v196, 16, v190
	v_and_b32_e32 v197, 0xffff0000, v190
	v_lshlrev_b32_e32 v190, 16, v191
	v_and_b32_e32 v191, 0xffff0000, v191
	v_lshlrev_b32_e32 v198, 16, v192
	v_and_b32_e32 v199, 0xffff0000, v192
	v_lshlrev_b32_e32 v192, 16, v193
	v_and_b32_e32 v193, 0xffff0000, v193
	v_pk_fma_f32 v[96:97], v[96:97], v[0:1], v[190:191] op_sel_hi:[1,0,1]
	v_pk_fma_f32 v[92:93], v[92:93], v[0:1], v[192:193] op_sel_hi:[1,0,1]
	v_lshlrev_b32_e32 v190, 16, v186
	v_and_b32_e32 v191, 0xffff0000, v186
	v_lshlrev_b32_e32 v186, 16, v187
	v_and_b32_e32 v187, 0xffff0000, v187
	v_lshlrev_b32_e32 v192, 16, v188
	v_and_b32_e32 v193, 0xffff0000, v188
	v_lshlrev_b32_e32 v188, 16, v189
	v_and_b32_e32 v189, 0xffff0000, v189
	v_pk_fma_f32 v[94:95], v[94:95], v[0:1], v[196:197] op_sel_hi:[1,0,1]
	v_pk_fma_f32 v[90:91], v[90:91], v[0:1], v[198:199] op_sel_hi:[1,0,1]
	v_pk_fma_f32 v[88:89], v[88:89], v[0:1], v[186:187] op_sel_hi:[1,0,1]
	v_pk_fma_f32 v[86:87], v[86:87], v[0:1], v[190:191] op_sel_hi:[1,0,1]
	v_pk_fma_f32 v[84:85], v[84:85], v[0:1], v[188:189] op_sel_hi:[1,0,1]
	v_pk_fma_f32 v[82:83], v[82:83], v[0:1], v[192:193] op_sel_hi:[1,0,1]
	v_fmamk_f32 v0, v195, 0x3a800000, v230
	v_cmp_gt_f32_e32 vcc, s80, v0
	v_mul_f32_e32 v186, 0x4f800000, v0
	v_pk_mul_f32 v[56:57], v[56:57], v[152:153]
	v_cndmask_b32_e32 v0, v0, v186, vcc
	v_sqrt_f32_e32 v186, v0
	v_pk_mul_f32 v[54:55], v[54:55], v[150:151]
	v_pk_mul_f32 v[52:53], v[52:53], v[144:145]
	v_pk_mul_f32 v[50:51], v[50:51], v[142:143]
	v_add_u32_e32 v187, -1, v186
	v_fma_f32 v188, -v187, v186, v0
	v_cmp_ge_f32_e64 s[14:15], 0, v188
	v_add_u32_e32 v188, 1, v186
	v_pk_mul_f32 v[48:49], v[48:49], v[160:161]
	v_cndmask_b32_e64 v187, v186, v187, s[14:15]
	v_fma_f32 v186, -v188, v186, v0
	v_cmp_lt_f32_e64 s[14:15], 0, v186
	v_pk_mul_f32 v[40:41], v[40:41], v[152:153]
	v_pk_mul_f32 v[44:45], v[44:45], v[156:157]
	v_cndmask_b32_e64 v186, v187, v188, s[14:15]
	v_mul_f32_e32 v187, 0x37800000, v186
	v_cndmask_b32_e32 v186, v186, v187, vcc
	v_cmp_class_f32_e32 vcc, v0, v231
	v_pk_mul_f32 v[46:47], v[46:47], v[158:159]
	v_pk_mul_f32 v[42:43], v[42:43], v[154:155]
	v_cndmask_b32_e32 v0, v186, v0, vcc
	v_div_scale_f32 v186, s[14:15], v0, v0, s31
	v_rcp_f32_e32 v187, v186
	v_pk_mul_f32 v[38:39], v[38:39], v[150:151]
	v_pk_mul_f32 v[36:37], v[36:37], v[144:145]
	v_pk_mul_f32 v[34:35], v[34:35], v[142:143]
	v_fma_f32 v188, -v186, v187, 1.0
	v_fmac_f32_e32 v187, v188, v187
	v_div_scale_f32 v188, vcc, s31, v0, s31
	v_mul_f32_e32 v189, v188, v187
	v_fma_f32 v190, -v186, v189, v188
	v_fmac_f32_e32 v189, v190, v187
	v_fma_f32 v186, -v186, v189, v188
	v_div_fmas_f32 v186, v186, v187, v189
	v_div_fixup_f32 v0, v186, v0, s31
	v_lshlrev_b32_e32 v186, 16, v182
	v_and_b32_e32 v187, 0xffff0000, v182
	v_lshlrev_b32_e32 v182, 16, v183
	v_and_b32_e32 v183, 0xffff0000, v183
	v_pk_fma_f32 v[80:81], v[80:81], v[0:1], v[182:183] op_sel_hi:[1,0,1]
	v_lshlrev_b32_e32 v182, 16, v178
	v_and_b32_e32 v183, 0xffff0000, v178
	v_lshlrev_b32_e32 v178, 16, v179
	v_and_b32_e32 v179, 0xffff0000, v179
	v_pk_fma_f32 v[72:73], v[72:73], v[0:1], v[178:179] op_sel_hi:[1,0,1]
	ds_read2_b32 v[178:179], v243 offset0:128 offset1:144
	v_lshlrev_b32_e32 v188, 16, v184
	v_and_b32_e32 v189, 0xffff0000, v184
	v_lshlrev_b32_e32 v184, 16, v185
	v_and_b32_e32 v185, 0xffff0000, v185
	v_pk_fma_f32 v[76:77], v[76:77], v[0:1], v[184:185] op_sel_hi:[1,0,1]
	v_lshlrev_b32_e32 v184, 16, v180
	v_and_b32_e32 v185, 0xffff0000, v180
	v_lshlrev_b32_e32 v180, 16, v181
	v_and_b32_e32 v181, 0xffff0000, v181
	v_pk_fma_f32 v[78:79], v[78:79], v[0:1], v[186:187] op_sel_hi:[1,0,1]
	v_pk_fma_f32 v[74:75], v[74:75], v[0:1], v[188:189] op_sel_hi:[1,0,1]
	v_pk_fma_f32 v[70:71], v[70:71], v[0:1], v[182:183] op_sel_hi:[1,0,1]
	v_pk_fma_f32 v[68:69], v[68:69], v[0:1], v[180:181] op_sel_hi:[1,0,1]
	v_pk_fma_f32 v[66:67], v[66:67], v[0:1], v[184:185] op_sel_hi:[1,0,1]
	s_waitcnt lgkmcnt(0)
;     __device__ __forceinline__ void run(f32x4 (&acc)[2][2][4][2], const Unit& u, int wr, int wc, int fr, int fq, PG8_LAS unsigned char* lds, int wid, int lane) const {
;     ...
;               for (int m = 0; m < 4; ++m) { const int r = ai * HALF + wr * 64 + m * 16 + fr; const float rs = coef / sqrtf(S[r] * (1.0f / 1024.0f) + 1e-6f);
; #pragma unroll
;                   for (int bj = 0; bj < 2; ++bj) { f32x4 x0, x1; unpack8(pre[ai][m][bj], x0, x1);
;                       acc[ai][bj][m][0] = x0 + acc[ai][bj][m][0] * g[bj][0] * rs; acc[ai][bj][m][1] = x1 + acc[ai][bj][m][1] * g[bj][1] * rs; } } }
	v_fmamk_f32 v0, v178, 0x3a800000, v230
	v_cmp_gt_f32_e32 vcc, s80, v0
	v_mul_f32_e32 v178, 0x4f800000, v0
	v_pk_mul_f32 v[32:33], v[32:33], v[160:161]
	v_cndmask_b32_e32 v0, v0, v178, vcc
	v_sqrt_f32_e32 v178, v0
	v_pk_mul_f32 v[28:29], v[28:29], v[156:157]
	v_pk_mul_f32 v[30:31], v[30:31], v[158:159]
	v_pk_mul_f32 v[26:27], v[26:27], v[154:155]
	v_add_u32_e32 v180, -1, v178
	v_fma_f32 v181, -v180, v178, v0
	v_cmp_ge_f32_e64 s[14:15], 0, v181
	v_add_u32_e32 v181, 1, v178
	v_pk_mul_f32 v[24:25], v[24:25], v[152:153]
	v_cndmask_b32_e64 v180, v178, v180, s[14:15]
	v_fma_f32 v178, -v181, v178, v0
	v_cmp_lt_f32_e64 s[14:15], 0, v178
	v_pk_mul_f32 v[22:23], v[22:23], v[150:151]
	v_pk_mul_f32 v[20:21], v[20:21], v[144:145]
	v_cndmask_b32_e64 v178, v180, v181, s[14:15]
	v_mul_f32_e32 v180, 0x37800000, v178
	v_cndmask_b32_e32 v178, v178, v180, vcc
	v_cmp_class_f32_e32 vcc, v0, v231
	v_pk_mul_f32 v[18:19], v[18:19], v[142:143]
	v_pk_mul_f32 v[16:17], v[16:17], v[160:161]
	v_cndmask_b32_e32 v0, v178, v0, vcc
	v_div_scale_f32 v178, s[14:15], v0, v0, s31
	v_rcp_f32_e32 v180, v178
	v_pk_mul_f32 v[12:13], v[12:13], v[156:157]
	v_pk_mul_f32 v[14:15], v[14:15], v[158:159]
	v_pk_mul_f32 v[10:11], v[10:11], v[154:155]
	v_fma_f32 v181, -v178, v180, 1.0
	v_fmac_f32_e32 v180, v181, v180
	v_div_scale_f32 v181, vcc, s31, v0, s31
	v_mul_f32_e32 v182, v181, v180
	v_fma_f32 v183, -v178, v182, v181
	v_fmac_f32_e32 v182, v183, v180
	v_fma_f32 v178, -v178, v182, v181
	v_div_fmas_f32 v178, v178, v180, v182
	v_div_fixup_f32 v0, v178, v0, s31
	v_lshlrev_b32_e32 v180, 16, v174
	v_and_b32_e32 v181, 0xffff0000, v174
	v_lshlrev_b32_e32 v174, 16, v175
	v_and_b32_e32 v175, 0xffff0000, v175
	v_lshlrev_b32_e32 v182, 16, v176
	v_and_b32_e32 v183, 0xffff0000, v176
	v_lshlrev_b32_e32 v176, 16, v177
	v_and_b32_e32 v177, 0xffff0000, v177
	v_pk_fma_f32 v[64:65], v[64:65], v[0:1], v[174:175] op_sel_hi:[1,0,1]
	v_pk_fma_f32 v[60:61], v[60:61], v[0:1], v[176:177] op_sel_hi:[1,0,1]
	v_lshlrev_b32_e32 v174, 16, v170
	v_and_b32_e32 v175, 0xffff0000, v170
	v_lshlrev_b32_e32 v170, 16, v171
	v_and_b32_e32 v171, 0xffff0000, v171
	v_lshlrev_b32_e32 v176, 16, v172
	v_and_b32_e32 v177, 0xffff0000, v172
	v_lshlrev_b32_e32 v172, 16, v173
	v_and_b32_e32 v173, 0xffff0000, v173
	v_pk_fma_f32 v[62:63], v[62:63], v[0:1], v[180:181] op_sel_hi:[1,0,1]
	v_pk_fma_f32 v[58:59], v[58:59], v[0:1], v[182:183] op_sel_hi:[1,0,1]
	v_pk_fma_f32 v[56:57], v[56:57], v[0:1], v[170:171] op_sel_hi:[1,0,1]
	v_pk_fma_f32 v[54:55], v[54:55], v[0:1], v[174:175] op_sel_hi:[1,0,1]
	v_pk_fma_f32 v[52:53], v[52:53], v[0:1], v[172:173] op_sel_hi:[1,0,1]
	v_pk_fma_f32 v[50:51], v[50:51], v[0:1], v[176:177] op_sel_hi:[1,0,1]
	v_fmamk_f32 v0, v179, 0x3a800000, v230
	v_cmp_gt_f32_e32 vcc, s80, v0
	v_mul_f32_e32 v170, 0x4f800000, v0
	v_pk_mul_f32 v[8:9], v[8:9], v[152:153]
	v_cndmask_b32_e32 v0, v0, v170, vcc
	v_sqrt_f32_e32 v170, v0
	v_pk_mul_f32 v[6:7], v[6:7], v[150:151]
	v_pk_mul_f32 v[4:5], v[4:5], v[144:145]
	v_pk_mul_f32 v[2:3], v[2:3], v[142:143]
	v_add_u32_e32 v171, -1, v170
	v_fma_f32 v172, -v171, v170, v0
	v_cmp_ge_f32_e64 s[14:15], 0, v172
	v_add_u32_e32 v172, 1, v170
	s_nop 0
	v_cndmask_b32_e64 v171, v170, v171, s[14:15]
	v_fma_f32 v170, -v172, v170, v0
	v_cmp_lt_f32_e64 s[14:15], 0, v170
	s_nop 1
	v_cndmask_b32_e64 v170, v171, v172, s[14:15]
	v_mul_f32_e32 v171, 0x37800000, v170
	v_cndmask_b32_e32 v170, v170, v171, vcc
	v_cmp_class_f32_e32 vcc, v0, v231
	s_nop 1
	v_cndmask_b32_e32 v0, v170, v0, vcc
	v_div_scale_f32 v170, s[14:15], v0, v0, s31
	v_rcp_f32_e32 v171, v170
	s_nop 0
	v_fma_f32 v172, -v170, v171, 1.0
	v_fmac_f32_e32 v171, v172, v171
	v_div_scale_f32 v172, vcc, s31, v0, s31
	v_mul_f32_e32 v173, v172, v171
	v_fma_f32 v174, -v170, v173, v172
	v_fmac_f32_e32 v173, v174, v171
	v_fma_f32 v170, -v170, v173, v172
	v_div_fmas_f32 v170, v170, v171, v173
	v_div_fixup_f32 v0, v170, v0, s31
	v_lshlrev_b32_e32 v170, 16, v166
	v_and_b32_e32 v171, 0xffff0000, v166
	v_lshlrev_b32_e32 v166, 16, v167
	v_and_b32_e32 v167, 0xffff0000, v167
	v_pk_fma_f32 v[48:49], v[48:49], v[0:1], v[166:167] op_sel_hi:[1,0,1]
	v_lshlrev_b32_e32 v166, 16, v162
	v_and_b32_e32 v167, 0xffff0000, v162
	v_lshlrev_b32_e32 v162, 16, v163
	v_and_b32_e32 v163, 0xffff0000, v163
	v_pk_fma_f32 v[40:41], v[40:41], v[0:1], v[162:163] op_sel_hi:[1,0,1]
	ds_read2_b32 v[162:163], v243 offset0:160 offset1:176
	v_lshlrev_b32_e32 v172, 16, v168
	v_and_b32_e32 v173, 0xffff0000, v168
	v_lshlrev_b32_e32 v168, 16, v169
	v_and_b32_e32 v169, 0xffff0000, v169
	v_pk_fma_f32 v[44:45], v[44:45], v[0:1], v[168:169] op_sel_hi:[1,0,1]
	v_lshlrev_b32_e32 v168, 16, v164
	v_and_b32_e32 v169, 0xffff0000, v164
	v_lshlrev_b32_e32 v164, 16, v165
	v_and_b32_e32 v165, 0xffff0000, v165
	v_pk_fma_f32 v[46:47], v[46:47], v[0:1], v[170:171] op_sel_hi:[1,0,1]
	v_pk_fma_f32 v[42:43], v[42:43], v[0:1], v[172:173] op_sel_hi:[1,0,1]
	v_pk_fma_f32 v[38:39], v[38:39], v[0:1], v[166:167] op_sel_hi:[1,0,1]
	v_pk_fma_f32 v[36:37], v[36:37], v[0:1], v[164:165] op_sel_hi:[1,0,1]
	v_pk_fma_f32 v[34:35], v[34:35], v[0:1], v[168:169] op_sel_hi:[1,0,1]
	s_waitcnt lgkmcnt(0)
;     __device__ __forceinline__ void run(f32x4 (&acc)[2][2][4][2], const Unit& u, int wr, int wc, int fr, int fq, PG8_LAS unsigned char* lds, int wid, int lane) const {
;     ...
;               for (int m = 0; m < 4; ++m) { const int r = ai * HALF + wr * 64 + m * 16 + fr; const float rs = coef / sqrtf(S[r] * (1.0f / 1024.0f) + 1e-6f);
; #pragma unroll
;                   for (int bj = 0; bj < 2; ++bj) { f32x4 x0, x1; unpack8(pre[ai][m][bj], x0, x1);
;                       acc[ai][bj][m][0] = x0 + acc[ai][bj][m][0] * g[bj][0] * rs; acc[ai][bj][m][1] = x1 + acc[ai][bj][m][1] * g[bj][1] * rs; } } }
;         if (!fout) panel_ss_publish(acc, u, wr, wc, fr, fq, lds, wid, lane, slots2, cnt2);
	v_fmamk_f32 v0, v162, 0x3a800000, v230
	v_cmp_gt_f32_e32 vcc, s80, v0
	v_mul_f32_e32 v162, 0x4f800000, v0
	s_nop 0
	v_cndmask_b32_e32 v0, v0, v162, vcc
	v_sqrt_f32_e32 v162, v0
	s_nop 0
	v_add_u32_e32 v164, -1, v162
	v_fma_f32 v165, -v164, v162, v0
	v_cmp_ge_f32_e64 s[14:15], 0, v165
	v_add_u32_e32 v165, 1, v162
	s_nop 0
	v_cndmask_b32_e64 v164, v162, v164, s[14:15]
	v_fma_f32 v162, -v165, v162, v0
	v_cmp_lt_f32_e64 s[14:15], 0, v162
	s_nop 1
	v_cndmask_b32_e64 v162, v164, v165, s[14:15]
	v_mul_f32_e32 v164, 0x37800000, v162
	v_cndmask_b32_e32 v162, v162, v164, vcc
	v_cmp_class_f32_e32 vcc, v0, v231
	s_nop 1
	v_cndmask_b32_e32 v0, v162, v0, vcc
	v_div_scale_f32 v162, s[14:15], v0, v0, s31
	v_rcp_f32_e32 v164, v162
	s_nop 0
	v_fma_f32 v165, -v162, v164, 1.0
	v_fmac_f32_e32 v164, v165, v164
	v_div_scale_f32 v165, vcc, s31, v0, s31
	v_mul_f32_e32 v166, v165, v164
	v_fma_f32 v167, -v162, v166, v165
	v_fmac_f32_e32 v166, v167, v164
	v_fma_f32 v162, -v162, v166, v165
	v_div_fmas_f32 v162, v162, v164, v166
	v_div_fixup_f32 v0, v162, v0, s31
	v_lshlrev_b32_e32 v164, 16, v146
	v_and_b32_e32 v165, 0xffff0000, v146
	v_lshlrev_b32_e32 v146, 16, v147
	v_and_b32_e32 v147, 0xffff0000, v147
	v_lshlrev_b32_e32 v166, 16, v148
	v_and_b32_e32 v167, 0xffff0000, v148
	v_lshlrev_b32_e32 v148, 16, v149
	v_and_b32_e32 v149, 0xffff0000, v149
	v_pk_fma_f32 v[32:33], v[32:33], v[0:1], v[146:147] op_sel_hi:[1,0,1]
	v_pk_fma_f32 v[28:29], v[28:29], v[0:1], v[148:149] op_sel_hi:[1,0,1]
	v_lshlrev_b32_e32 v146, 16, v138
	v_and_b32_e32 v147, 0xffff0000, v138
	v_lshlrev_b32_e32 v138, 16, v139
	v_and_b32_e32 v139, 0xffff0000, v139
	v_lshlrev_b32_e32 v148, 16, v140
	v_and_b32_e32 v149, 0xffff0000, v140
	v_lshlrev_b32_e32 v140, 16, v141
	v_and_b32_e32 v141, 0xffff0000, v141
	v_pk_fma_f32 v[30:31], v[30:31], v[0:1], v[164:165] op_sel_hi:[1,0,1]
	v_pk_fma_f32 v[26:27], v[26:27], v[0:1], v[166:167] op_sel_hi:[1,0,1]
	v_pk_fma_f32 v[24:25], v[24:25], v[0:1], v[138:139] op_sel_hi:[1,0,1]
	v_pk_fma_f32 v[22:23], v[22:23], v[0:1], v[146:147] op_sel_hi:[1,0,1]
	v_pk_fma_f32 v[20:21], v[20:21], v[0:1], v[140:141] op_sel_hi:[1,0,1]
	v_pk_fma_f32 v[18:19], v[18:19], v[0:1], v[148:149] op_sel_hi:[1,0,1]
	v_fmamk_f32 v0, v163, 0x3a800000, v230
	v_cmp_gt_f32_e32 vcc, s80, v0
	v_mul_f32_e32 v138, 0x4f800000, v0
	s_nop 0
	v_cndmask_b32_e32 v0, v0, v138, vcc
	v_sqrt_f32_e32 v138, v0
	s_nop 0
	v_add_u32_e32 v139, -1, v138
	v_fma_f32 v140, -v139, v138, v0
	v_cmp_ge_f32_e64 s[14:15], 0, v140
	v_add_u32_e32 v140, 1, v138
	s_nop 0
	v_cndmask_b32_e64 v139, v138, v139, s[14:15]
	v_fma_f32 v138, -v140, v138, v0
	v_cmp_lt_f32_e64 s[14:15], 0, v138
	s_nop 1
	v_cndmask_b32_e64 v138, v139, v140, s[14:15]
	v_mul_f32_e32 v139, 0x37800000, v138
	v_cndmask_b32_e32 v138, v138, v139, vcc
	v_cmp_class_f32_e32 vcc, v0, v231
	s_nop 1
	v_cndmask_b32_e32 v0, v138, v0, vcc
	v_div_scale_f32 v138, s[14:15], v0, v0, s31
	v_rcp_f32_e32 v139, v138
	s_cselect_b64 s[14:15], -1, 0
	v_fma_f32 v140, -v138, v139, 1.0
	v_fmac_f32_e32 v139, v140, v139
	v_div_scale_f32 v140, vcc, s31, v0, s31
	v_mul_f32_e32 v141, v140, v139
	v_fma_f32 v146, -v138, v141, v140
	v_fmac_f32_e32 v141, v146, v139
	v_fma_f32 v138, -v138, v141, v140
	v_div_fmas_f32 v138, v138, v139, v141
	v_div_fixup_f32 v0, v138, v0, s31
	v_lshlrev_b32_e32 v138, 16, v134
	v_and_b32_e32 v139, 0xffff0000, v134
	v_lshlrev_b32_e32 v134, 16, v135
	v_and_b32_e32 v135, 0xffff0000, v135
	v_lshlrev_b32_e32 v140, 16, v136
	v_and_b32_e32 v141, 0xffff0000, v136
	v_lshlrev_b32_e32 v136, 16, v137
	v_and_b32_e32 v137, 0xffff0000, v137
	v_pk_fma_f32 v[16:17], v[16:17], v[0:1], v[134:135] op_sel_hi:[1,0,1]
	v_pk_fma_f32 v[12:13], v[12:13], v[0:1], v[136:137] op_sel_hi:[1,0,1]
	v_lshlrev_b32_e32 v134, 16, v130
	v_and_b32_e32 v135, 0xffff0000, v130
	v_lshlrev_b32_e32 v130, 16, v131
	v_and_b32_e32 v131, 0xffff0000, v131
	v_lshlrev_b32_e32 v136, 16, v132
	v_and_b32_e32 v137, 0xffff0000, v132
	v_lshlrev_b32_e32 v132, 16, v133
	v_and_b32_e32 v133, 0xffff0000, v133
	v_pk_fma_f32 v[14:15], v[14:15], v[0:1], v[138:139] op_sel_hi:[1,0,1]
	v_pk_fma_f32 v[10:11], v[10:11], v[0:1], v[140:141] op_sel_hi:[1,0,1]
	v_pk_fma_f32 v[8:9], v[8:9], v[0:1], v[130:131] op_sel_hi:[1,0,1]
	v_pk_fma_f32 v[6:7], v[6:7], v[0:1], v[134:135] op_sel_hi:[1,0,1]
	v_pk_fma_f32 v[4:5], v[4:5], v[0:1], v[132:133] op_sel_hi:[1,0,1]
	v_pk_fma_f32 v[2:3], v[2:3], v[0:1], v[136:137] op_sel_hi:[1,0,1]
	s_and_b64 vcc, exec, s[14:15]
	s_cbranch_vccnz .LBB0_203
; __device__ __forceinline__ float shx(float v, int o, int lane) { return __builtin_bit_cast(float, __builtin_amdgcn_ds_bpermute((lane ^ o) << 2, __builtin_bit_cast(int, v))); }
; #define PG8_LAS __attribute__((address_space(3)))
; __device__ __forceinline__ void panel_ss_publish(const f32x4 (&v)[2][2][4][2], const Unit& u, int wr, int wc, int fr, int fq, PG8_LAS unsigned char* lds, int wid, int lane, float* slots, unsigned* cnt) {
;     PG8_LAS float* P = (PG8_LAS float*)lds;
; #pragma unroll
;     for (int ai = 0; ai < 2; ++ai)
; #pragma unroll
;         for (int m = 0; m < 4; ++m) { float s = 0.f;
; #pragma unroll
;             for (int bj = 0; bj < 2; ++bj)
; #pragma unroll
;                 for (int n = 0; n < 2; ++n) { const f32x4 x = v[ai][bj][m][n]; s += (x[0] * x[0] + x[1] * x[1]) + (x[2] * x[2] + x[3] * x[3]); }
;             s += shx(s, 16, lane); s += shx(s, 32, lane);
;             if (fq == 0) P[(ai * HALF + wr * 64 + m * 16 + fr) * 4 + wc] = s; }
	s_lshl_b32 s4, s57, 10
	s_add_i32 s4, s36, s4
	v_mul_f32_e32 v132, v127, v127
	v_mul_f32_e32 v131, v129, v129
	v_fmac_f32_e32 v132, v126, v126
	v_fmac_f32_e32 v131, v128, v128
	v_add_f32_e32 v132, v132, v131
	v_mul_f32_e32 v130, v123, v123
	v_mul_f32_e32 v131, v125, v125
	v_fmac_f32_e32 v130, v122, v122
	v_fmac_f32_e32 v131, v124, v124
	v_add_f32_e32 v130, v130, v131
	v_add_f32_e32 v132, v130, v132
	v_mul_f32_e32 v130, v119, v119
	v_mul_f32_e32 v131, v121, v121
	v_fmac_f32_e32 v130, v118, v118
	v_fmac_f32_e32 v131, v120, v120
	v_add_f32_e32 v130, v130, v131
	v_add_f32_e32 v132, v130, v132
	v_mul_f32_e32 v130, v115, v115
	v_mul_f32_e32 v131, v117, v117
	v_fmac_f32_e32 v130, v114, v114
	v_fmac_f32_e32 v131, v116, v116
	v_add_f32_e32 v130, v130, v131
	v_add_f32_e32 v132, v130, v132
	ds_bpermute_b32 v140, v240, v132
	v_mul_f32_e32 v133, v111, v111
	v_mul_f32_e32 v131, v113, v113
	v_fmac_f32_e32 v133, v110, v110
	v_fmac_f32_e32 v131, v112, v112
	v_add_f32_e32 v133, v133, v131
	v_mul_f32_e32 v130, v107, v107
	v_mul_f32_e32 v131, v109, v109
	v_fmac_f32_e32 v130, v106, v106
	v_fmac_f32_e32 v131, v108, v108
	v_add_f32_e32 v130, v130, v131
	v_add_f32_e32 v133, v130, v133
	v_mul_f32_e32 v130, v103, v103
	v_mul_f32_e32 v131, v105, v105
	v_fmac_f32_e32 v130, v102, v102
	v_fmac_f32_e32 v131, v104, v104
	v_add_f32_e32 v130, v130, v131
	v_add_f32_e32 v133, v130, v133
	v_mul_f32_e32 v130, v99, v99
	v_mul_f32_e32 v131, v101, v101
	v_fmac_f32_e32 v130, v98, v98
	v_fmac_f32_e32 v131, v100, v100
	v_add_f32_e32 v130, v130, v131
	v_add_f32_e32 v133, v130, v133
	ds_bpermute_b32 v141, v240, v133
	v_mul_f32_e32 v134, v95, v95
	v_mul_f32_e32 v131, v97, v97
	v_fmac_f32_e32 v134, v94, v94
	v_fmac_f32_e32 v131, v96, v96
	v_add_f32_e32 v134, v134, v131
	v_mul_f32_e32 v130, v91, v91
	v_mul_f32_e32 v131, v93, v93
	v_fmac_f32_e32 v130, v90, v90
	v_fmac_f32_e32 v131, v92, v92
	v_add_f32_e32 v130, v130, v131
	v_add_f32_e32 v134, v130, v134
	v_mul_f32_e32 v130, v87, v87
	v_mul_f32_e32 v131, v89, v89
	v_fmac_f32_e32 v130, v86, v86
	v_fmac_f32_e32 v131, v88, v88
	v_add_f32_e32 v130, v130, v131
	v_add_f32_e32 v134, v130, v134
	v_mul_f32_e32 v130, v83, v83
	v_mul_f32_e32 v131, v85, v85
	v_fmac_f32_e32 v130, v82, v82
	v_fmac_f32_e32 v131, v84, v84
	v_add_f32_e32 v130, v130, v131
	v_add_f32_e32 v134, v130, v134
	ds_bpermute_b32 v142, v240, v134
	v_mul_f32_e32 v135, v79, v79
	v_mul_f32_e32 v131, v81, v81
	v_fmac_f32_e32 v135, v78, v78
	v_fmac_f32_e32 v131, v80, v80
	v_add_f32_e32 v135, v135, v131
	v_mul_f32_e32 v130, v75, v75
	v_mul_f32_e32 v131, v77, v77
	v_fmac_f32_e32 v130, v74, v74
	v_fmac_f32_e32 v131, v76, v76
	v_add_f32_e32 v130, v130, v131
	v_add_f32_e32 v135, v130, v135
	v_mul_f32_e32 v130, v71, v71
	v_mul_f32_e32 v131, v73, v73
	v_fmac_f32_e32 v130, v70, v70
	v_fmac_f32_e32 v131, v72, v72
	v_add_f32_e32 v130, v130, v131
	v_add_f32_e32 v135, v130, v135
	v_mul_f32_e32 v130, v67, v67
	v_mul_f32_e32 v131, v69, v69
	v_fmac_f32_e32 v130, v66, v66
	v_fmac_f32_e32 v131, v68, v68
	v_add_f32_e32 v130, v130, v131
	v_add_f32_e32 v135, v130, v135
	ds_bpermute_b32 v143, v240, v135
	v_mul_f32_e32 v136, v63, v63
	v_mul_f32_e32 v131, v65, v65
	v_fmac_f32_e32 v136, v62, v62
	v_fmac_f32_e32 v131, v64, v64
	v_add_f32_e32 v136, v136, v131
	v_mul_f32_e32 v130, v59, v59
	v_mul_f32_e32 v131, v61, v61
	v_fmac_f32_e32 v130, v58, v58
	v_fmac_f32_e32 v131, v60, v60
	v_add_f32_e32 v130, v130, v131
	v_add_f32_e32 v136, v130, v136
	v_mul_f32_e32 v130, v55, v55
	v_mul_f32_e32 v131, v57, v57
	v_fmac_f32_e32 v130, v54, v54
	v_fmac_f32_e32 v131, v56, v56
	v_add_f32_e32 v130, v130, v131
	v_add_f32_e32 v136, v130, v136
	v_mul_f32_e32 v130, v51, v51
	v_mul_f32_e32 v131, v53, v53
	v_fmac_f32_e32 v130, v50, v50
	v_fmac_f32_e32 v131, v52, v52
	v_add_f32_e32 v130, v130, v131
	v_add_f32_e32 v136, v130, v136
	ds_bpermute_b32 v144, v240, v136
	v_mul_f32_e32 v137, v47, v47
	v_mul_f32_e32 v131, v49, v49
	v_fmac_f32_e32 v137, v46, v46
	v_fmac_f32_e32 v131, v48, v48
	v_add_f32_e32 v137, v137, v131
	v_mul_f32_e32 v130, v43, v43
	v_mul_f32_e32 v131, v45, v45
	v_fmac_f32_e32 v130, v42, v42
	v_fmac_f32_e32 v131, v44, v44
	v_add_f32_e32 v130, v130, v131
	v_add_f32_e32 v137, v130, v137
	v_mul_f32_e32 v130, v39, v39
	v_mul_f32_e32 v131, v41, v41
	v_fmac_f32_e32 v130, v38, v38
	v_fmac_f32_e32 v131, v40, v40
	v_add_f32_e32 v130, v130, v131
	v_add_f32_e32 v137, v130, v137
	v_mul_f32_e32 v130, v35, v35
	v_mul_f32_e32 v131, v37, v37
	v_fmac_f32_e32 v130, v34, v34
	v_fmac_f32_e32 v131, v36, v36
	v_add_f32_e32 v130, v130, v131
	v_add_f32_e32 v137, v130, v137
	ds_bpermute_b32 v145, v240, v137
	v_mul_f32_e32 v138, v31, v31
	v_mul_f32_e32 v131, v33, v33
	v_fmac_f32_e32 v138, v30, v30
	v_fmac_f32_e32 v131, v32, v32
	v_add_f32_e32 v138, v138, v131
	v_mul_f32_e32 v130, v27, v27
	v_mul_f32_e32 v131, v29, v29
	v_fmac_f32_e32 v130, v26, v26
	v_fmac_f32_e32 v131, v28, v28
	v_add_f32_e32 v130, v130, v131
	v_add_f32_e32 v138, v130, v138
	v_mul_f32_e32 v130, v23, v23
	v_mul_f32_e32 v131, v25, v25
	v_fmac_f32_e32 v130, v22, v22
	v_fmac_f32_e32 v131, v24, v24
	v_add_f32_e32 v130, v130, v131
	v_add_f32_e32 v138, v130, v138
	v_mul_f32_e32 v130, v19, v19
	v_mul_f32_e32 v131, v21, v21
	v_fmac_f32_e32 v130, v18, v18
	v_fmac_f32_e32 v131, v20, v20
	v_add_f32_e32 v130, v130, v131
	v_add_f32_e32 v138, v130, v138
	ds_bpermute_b32 v146, v240, v138
	v_mul_f32_e32 v139, v15, v15
	v_mul_f32_e32 v131, v17, v17
	v_fmac_f32_e32 v139, v14, v14
	v_fmac_f32_e32 v131, v16, v16
	v_add_f32_e32 v139, v139, v131
	v_mul_f32_e32 v130, v11, v11
	v_mul_f32_e32 v131, v13, v13
	v_fmac_f32_e32 v130, v10, v10
	v_fmac_f32_e32 v131, v12, v12
	v_add_f32_e32 v130, v130, v131
	v_add_f32_e32 v139, v130, v139
	v_mul_f32_e32 v130, v7, v7
	v_mul_f32_e32 v131, v9, v9
	v_fmac_f32_e32 v130, v6, v6
	v_fmac_f32_e32 v131, v8, v8
	v_add_f32_e32 v130, v130, v131
	v_add_f32_e32 v139, v130, v139
	v_mul_f32_e32 v130, v3, v3
	v_mul_f32_e32 v131, v5, v5
	v_fmac_f32_e32 v130, v2, v2
	v_fmac_f32_e32 v131, v4, v4
	v_add_f32_e32 v130, v130, v131
	v_add_f32_e32 v139, v130, v139
	ds_bpermute_b32 v147, v240, v139
	s_waitcnt lgkmcnt(0)
	v_add_f32_e32 v132, v132, v140
	ds_bpermute_b32 v140, v241, v132
	v_add_f32_e32 v133, v133, v141
	ds_bpermute_b32 v141, v241, v133
	v_add_f32_e32 v134, v134, v142
	ds_bpermute_b32 v142, v241, v134
	v_add_f32_e32 v135, v135, v143
	ds_bpermute_b32 v143, v241, v135
	v_add_f32_e32 v136, v136, v144
	ds_bpermute_b32 v144, v241, v136
	v_add_f32_e32 v137, v137, v145
	ds_bpermute_b32 v145, v241, v137
	v_add_f32_e32 v138, v138, v146
	ds_bpermute_b32 v146, v241, v138
	v_add_f32_e32 v139, v139, v147
	ds_bpermute_b32 v147, v241, v139
	s_and_saveexec_b64 s[30:31], s[6:7]
	s_cbranch_execz .Lpub1_skip
; __device__ __forceinline__ float shx(float v, int o, int lane) { return __builtin_bit_cast(float, __builtin_amdgcn_ds_bpermute((lane ^ o) << 2, __builtin_bit_cast(int, v))); }
; __device__ __forceinline__ void panel_ss_publish(const f32x4 (&v)[2][2][4][2], const Unit& u, int wr, int wc, int fr, int fq, PG8_LAS unsigned char* lds, int wid, int lane, float* slots, unsigned* cnt) {
;     ...
;             s += shx(s, 16, lane); s += shx(s, 32, lane);
;             if (fq == 0) P[(ai * HALF + wr * 64 + m * 16 + fr) * 4 + wc] = s; }
	s_waitcnt lgkmcnt(0)
	v_lshl_add_u32 v130, v238, 4, s4
	v_add_f32_e32 v132, v132, v140
	ds_write_b32 v130, v132
	v_add_f32_e32 v133, v133, v141
	ds_write_b32 v130, v133 offset:256
	v_add_f32_e32 v134, v134, v142
	ds_write_b32 v130, v134 offset:512
	v_add_f32_e32 v135, v135, v143
	ds_write_b32 v130, v135 offset:768
	v_add_f32_e32 v136, v136, v144
	ds_write_b32 v130, v136 offset:2048
	v_add_f32_e32 v137, v137, v145
	ds_write_b32 v130, v137 offset:2304
	v_add_f32_e32 v138, v138, v146
	ds_write_b32 v130, v138 offset:2560
	v_add_f32_e32 v139, v139, v147
	ds_write_b32 v130, v139 offset:2816
